# code placement: all six GEMM K-loop heads at 16 mod 64 (the residue that probed best for the projection and FFN-in loops), aligned MFMA groups
# baseline (speedup 1.0000x reference)
; template <class Epi, class Sched, bool ALIGN_EPI = false, bool SP2 = false>
; __device__ __forceinline__ void gemm_phase(PG8_LAS unsigned char* lds, const Gemm g, const Sched& S, const Epi& E, int wave_s) {
;     ...
;         const bool has_next = S.next(ui + 1, nxt);
;         const char* nA = has_next ? (const char*)g.A + (size_t)nxt.pm * tstepA : cA; const char* nB = has_next ? (const char*)g.Bt + (size_t)nxt.pn * tstepB : cB;
;     ...
;         for (int a = 0; a < 2; ++a)
; #pragma unroll
;             for (int b = 0; b < 2; ++b)
; #pragma unroll
;                 for (int m = 0; m < 4; ++m)
; #pragma unroll
;                     for (int n = 0; n < 2; ++n) acc[a][b][m][n] = (f32x4){0.f, 0.f, 0.f, 0.f};
.LBB0_191:
	s_ashr_i32 s23, s22, 31
	s_lshl_b64 s[24:25], s[22:23], 20
	s_add_u32 s24, s2, s24
	s_addc_u32 s25, s30, s25
	s_and_b64 s[36:37], s[34:35], exec
	s_cselect_b32 s23, s25, s27
	s_cselect_b32 s39, s24, s26
	s_ashr_i32 s21, s20, 31
	s_lshl_b64 s[36:37], s[20:21], 20
	s_add_u32 s40, s42, s36
	s_addc_u32 s41, s43, s37
	s_and_b64 s[36:37], s[34:35], exec
	s_cselect_b32 s21, s41, s19
	s_cselect_b32 s52, s40, s18
	s_add_u32 s53, s18, 0x100
	s_addc_u32 s54, s19, 0
	s_add_u32 s18, s26, 0x80080
	s_addc_u32 s19, s27, 0
	s_mov_b32 s55, -2
	s_waitcnt vmcnt(0) lgkmcnt(0)
	s_nop 0
	s_nop 0
	s_nop 0
	s_nop 0
	s_nop 0
	s_nop 0
	s_nop 0
	s_nop 0
	v_mov_b64_e32 v[4:5], 0
	v_mov_b64_e32 v[6:7], 0
	v_mov_b64_e32 v[8:9], 0
	v_mov_b64_e32 v[10:11], 0
	v_mov_b64_e32 v[12:13], 0
	v_mov_b64_e32 v[14:15], 0
	v_mov_b64_e32 v[16:17], 0
	v_mov_b64_e32 v[18:19], 0
	v_mov_b64_e32 v[20:21], 0
	v_mov_b64_e32 v[22:23], 0
	v_mov_b64_e32 v[24:25], 0
	v_mov_b64_e32 v[26:27], 0
	v_mov_b64_e32 v[28:29], 0
	v_mov_b64_e32 v[30:31], 0
	v_mov_b64_e32 v[32:33], 0
	v_mov_b64_e32 v[34:35], 0
	v_mov_b64_e32 v[36:37], 0
	v_mov_b64_e32 v[38:39], 0
	v_mov_b64_e32 v[40:41], 0
	v_mov_b64_e32 v[42:43], 0
	v_mov_b64_e32 v[44:45], 0
	v_mov_b64_e32 v[46:47], 0
	v_mov_b64_e32 v[48:49], 0
	v_mov_b64_e32 v[50:51], 0
	v_mov_b64_e32 v[52:53], 0
	v_mov_b64_e32 v[54:55], 0
	v_mov_b64_e32 v[56:57], 0
	v_mov_b64_e32 v[58:59], 0
	v_mov_b64_e32 v[60:61], 0
	v_mov_b64_e32 v[62:63], 0
	v_mov_b64_e32 v[64:65], 0
	v_mov_b64_e32 v[66:67], 0
	v_mov_b64_e32 v[68:69], 0
	v_mov_b64_e32 v[70:71], 0
	v_mov_b64_e32 v[72:73], 0
	v_mov_b64_e32 v[74:75], 0
	v_mov_b64_e32 v[76:77], 0
	v_mov_b64_e32 v[78:79], 0
	v_mov_b64_e32 v[80:81], 0
	v_mov_b64_e32 v[82:83], 0
	v_mov_b64_e32 v[84:85], 0
	v_mov_b64_e32 v[86:87], 0
	v_mov_b64_e32 v[88:89], 0
	v_mov_b64_e32 v[90:91], 0
	v_mov_b64_e32 v[92:93], 0
	v_mov_b64_e32 v[94:95], 0
	v_mov_b64_e32 v[96:97], 0
	v_mov_b64_e32 v[98:99], 0
	v_mov_b64_e32 v[100:101], 0
	v_mov_b64_e32 v[102:103], 0
	v_mov_b64_e32 v[104:105], 0
	v_mov_b64_e32 v[106:107], 0
	v_mov_b64_e32 v[108:109], 0
	v_mov_b64_e32 v[110:111], 0
	v_mov_b64_e32 v[112:113], 0
	v_mov_b64_e32 v[114:115], 0
	v_mov_b64_e32 v[116:117], 0
	v_mov_b64_e32 v[118:119], 0
	v_mov_b64_e32 v[120:121], 0
	v_mov_b64_e32 v[122:123], 0
	v_mov_b64_e32 v[124:125], 0
	v_mov_b64_e32 v[126:127], 0
	v_mov_b64_e32 v[128:129], 0
	v_mov_b64_e32 v[130:131], 0

; #define PG8_STAGE(bufoff, gbase, voff) do { _Pragma("unroll") for (int _i = 0; _i < 2; ++_i) \
;         __builtin_amdgcn_global_load_lds((const unsigned*)((const char*)(gbase) + (voff)[_i]), (PG8_LAS unsigned*)(lds + (bufoff) + ldsw + _i * 8192), 16, 0, 0); } while (0)
; #define PG8_LDA(dst, b, h) do { _Pragma("unroll") for (int m = 0; m < 4; ++m) _Pragma("unroll") for (int k = 0; k < 2; ++k) dst[m][k] = *(const PG8_LAS bf16x8*)(lds + PG8_SA(b, h) + aoff + m * 2048 + k * 1024); } while (0)
; #define PG8_LDB(dst, b, h) do { _Pragma("unroll") for (int n = 0; n < 2; ++n) _Pragma("unroll") for (int k = 0; k < 2; ++k) dst[n][k] = *(const PG8_LAS bf16x8*)(lds + PG8_SB(b, h) + boff + n * 2048 + k * 1024); } while (0)
; #define PG8_WAIT_V(n) asm volatile("s_waitcnt vmcnt(" #n ")" ::: "memory")
; #define PG8_WAIT_L(n) asm volatile("s_waitcnt lgkmcnt(" #n ")" ::: "memory")
; #define PG8_BAR __builtin_amdgcn_s_barrier()
; #define PG8_SCHED __builtin_amdgcn_sched_barrier(0)
; template <class Epi, class Sched, bool ALIGN_EPI = false, bool SP2 = false>
; __device__ __forceinline__ void gemm_phase(PG8_LAS unsigned char* lds, const Gemm g, const Sched& S, const Epi& E, int wave_s) {
;     ...
;         const bool has_next = S.next(ui + 1, nxt);
;         const char* nA = has_next ? (const char*)g.A + (size_t)nxt.pm * tstepA : cA; const char* nB = has_next ? (const char*)g.Bt + (size_t)nxt.pn * tstepB : cB;
;         for (int t = 0; t < nt; t += 2) {
;             const bool last = (t == nt - 2);
;             const char* a1 = cA + (size_t)(t + 1) * kstep;
;             const char* a2 = last ? nA : cA + (size_t)(t + 2) * kstep; const char* b2 = last ? nB : cB + (size_t)(t + 2) * kstep;
;             const char* a3 = a2 + kstep; const char* b3 = b2 + kstep;
;             if (last && has_next) S.a_ready(nxt);
;             if constexpr (SP2) {
;             PG8_LDB(B0, 0, 0); PG8_LDB(B1, 0, 1); PG8_SCHED; PG8_LDA(At, 0, 0); PG8_STAGE(PG8_SA(1, 1), a1 + hstepA, voffA);
;             PG8_WAIT_V(8); PG8_WAIT_L(0); PG8_BAR; PG8_MMA(0, 0, At, B0); PG8_MMA(0, 1, At, B1); PG8_BAR; PG8_SCHED;
;     ...
;         for (int a = 0; a < 2; ++a)
; #pragma unroll
;             for (int b = 0; b < 2; ++b)
; #pragma unroll
;                 for (int m = 0; m < 4; ++m)
; #pragma unroll
;                     for (int n = 0; n < 2; ++n) acc[a][b][m][n] = (f32x4){0.f, 0.f, 0.f, 0.f};
.LBB0_567:
	s_ashr_i32 s19, s18, 31
	s_lshl_b64 s[22:23], s[18:19], 18
	s_add_u32 s22, s46, s22
	s_addc_u32 s23, s47, s23
	s_and_b64 s[38:39], s[38:39], exec
	s_cselect_b32 s19, s23, s27
	s_cselect_b32 s58, s22, s26
	s_add_u32 s59, s26, 0x100
	s_addc_u32 s66, s27, 0
	s_mov_b32 s67, -2
	s_waitcnt vmcnt(0) lgkmcnt(0)
	s_nop 0
	s_nop 0
	s_nop 0
	s_nop 0
	s_nop 0
	s_nop 0
	s_nop 0
	s_nop 0
	s_nop 0
	s_nop 0
	s_nop 0
	s_nop 0
	s_nop 0
	v_mov_b64_e32 v[4:5], 0
	v_mov_b64_e32 v[6:7], 0
	v_mov_b64_e32 v[8:9], 0
	v_mov_b64_e32 v[10:11], 0
	v_mov_b64_e32 v[12:13], 0
	v_mov_b64_e32 v[14:15], 0
	v_mov_b64_e32 v[16:17], 0
	v_mov_b64_e32 v[18:19], 0
	v_mov_b64_e32 v[20:21], 0
	v_mov_b64_e32 v[22:23], 0
	v_mov_b64_e32 v[24:25], 0
	v_mov_b64_e32 v[26:27], 0
	v_mov_b64_e32 v[28:29], 0
	v_mov_b64_e32 v[30:31], 0
	v_mov_b64_e32 v[32:33], 0
	v_mov_b64_e32 v[34:35], 0
	v_mov_b64_e32 v[36:37], 0
	v_mov_b64_e32 v[38:39], 0
	v_mov_b64_e32 v[40:41], 0
	v_mov_b64_e32 v[42:43], 0
	v_mov_b64_e32 v[44:45], 0
	v_mov_b64_e32 v[46:47], 0
	v_mov_b64_e32 v[48:49], 0
	v_mov_b64_e32 v[50:51], 0
	v_mov_b64_e32 v[52:53], 0
	v_mov_b64_e32 v[54:55], 0
	v_mov_b64_e32 v[56:57], 0
	v_mov_b64_e32 v[58:59], 0
	v_mov_b64_e32 v[60:61], 0
	v_mov_b64_e32 v[62:63], 0
	v_mov_b64_e32 v[64:65], 0
	v_mov_b64_e32 v[66:67], 0
	v_mov_b64_e32 v[68:69], 0
	v_mov_b64_e32 v[70:71], 0
	v_mov_b64_e32 v[72:73], 0
	v_mov_b64_e32 v[74:75], 0
	v_mov_b64_e32 v[76:77], 0
	v_mov_b64_e32 v[78:79], 0
	v_mov_b64_e32 v[80:81], 0
	v_mov_b64_e32 v[82:83], 0
	v_mov_b64_e32 v[84:85], 0
	v_mov_b64_e32 v[86:87], 0
	v_mov_b64_e32 v[88:89], 0
	v_mov_b64_e32 v[90:91], 0
	v_mov_b64_e32 v[92:93], 0
	v_mov_b64_e32 v[94:95], 0
	v_mov_b64_e32 v[96:97], 0
	v_mov_b64_e32 v[98:99], 0
	v_mov_b64_e32 v[100:101], 0
	v_mov_b64_e32 v[102:103], 0
	v_mov_b64_e32 v[104:105], 0
	v_mov_b64_e32 v[106:107], 0
	v_mov_b64_e32 v[108:109], 0
	v_mov_b64_e32 v[110:111], 0
	v_mov_b64_e32 v[112:113], 0
	v_mov_b64_e32 v[114:115], 0
	v_mov_b64_e32 v[116:117], 0
	v_mov_b64_e32 v[118:119], 0
	v_mov_b64_e32 v[120:121], 0
	v_mov_b64_e32 v[122:123], 0
	v_mov_b64_e32 v[124:125], 0
	v_mov_b64_e32 v[126:127], 0
	v_mov_b64_e32 v[128:129], 0
	v_mov_b64_e32 v[130:131], 0
.LBB0_568:
	s_add_u32 s26, s24, 0x100
	s_addc_u32 s27, s25, 0
	s_add_i32 s74, 0, 0x10000
	s_cmp_eq_u32 s67, 4
	s_cselect_b32 s43, s21, s27
	s_cselect_b32 s42, s20, s26
	s_cselect_b32 s39, s19, s66
	s_cselect_b32 s38, s58, s59
	s_add_i32 s75, 0, 0x14000
	v_add_u32_e32 v144, s74, v186
	v_add_u32_e32 v182, s75, v186
	ds_read_b128 v[132:135], v144
	ds_read_b128 v[136:139], v144 offset:1024
	ds_read_b128 v[140:143], v144 offset:2048
	ds_read_b128 v[144:147], v144 offset:3072
	ds_read_b128 v[148:151], v182
	ds_read_b128 v[160:163], v182 offset:1024
	ds_read_b128 v[164:167], v182 offset:2048
	ds_read_b128 v[182:185], v182 offset:3072
	v_lshl_add_u64 v[232:233], s[24:25], 0, v[158:159]
	s_add_i32 m0, s49, 0xc000
	ds_read_b128 v[190:193], v188
	ds_read_b128 v[194:197], v188 offset:1024
	ds_read_b128 v[198:201], v188 offset:2048
	ds_read_b128 v[212:215], v188 offset:3072
	ds_read_b128 v[216:219], v188 offset:4096
	ds_read_b128 v[220:223], v188 offset:5120
	ds_read_b128 v[224:227], v188 offset:6144
	ds_read_b128 v[228:231], v188 offset:7168
	global_load_lds_dwordx4 v[232:233], off
	v_lshl_add_u64 v[232:233], s[24:25], 0, v[156:157]
	s_add_i32 m0, s49, 0xe000
	s_nop 0
	global_load_lds_dwordx4 v[232:233], off
	s_waitcnt vmcnt(8)
	s_waitcnt lgkmcnt(0)
	s_barrier
	s_setprio 1
	s_waitcnt lgkmcnt(0)
	v_mfma_f32_16x16x32_bf16 v[128:131], v[132:135], v[190:193], v[128:131]
	v_mfma_f32_16x16x32_bf16 v[124:127], v[140:143], v[190:193], v[124:127]
	v_mfma_f32_16x16x32_bf16 v[120:123], v[132:135], v[198:201], v[120:123]
	v_mfma_f32_16x16x32_bf16 v[112:115], v[140:143], v[198:201], v[112:115]
	v_mfma_f32_16x16x32_bf16 v[100:103], v[132:135], v[216:219], v[100:103]
	v_mfma_f32_16x16x32_bf16 v[92:95], v[140:143], v[216:219], v[92:95]
	v_mfma_f32_16x16x32_bf16 v[84:87], v[132:135], v[224:227], v[84:87]
	v_mfma_f32_16x16x32_bf16 v[76:79], v[140:143], v[224:227], v[76:79]
	v_mfma_f32_16x16x32_bf16 v[128:131], v[136:139], v[194:197], v[128:131]
	v_mfma_f32_16x16x32_bf16 v[124:127], v[144:147], v[194:197], v[124:127]
	v_mfma_f32_16x16x32_bf16 v[120:123], v[136:139], v[212:215], v[120:123]
	v_mfma_f32_16x16x32_bf16 v[112:115], v[144:147], v[212:215], v[112:115]
	v_mfma_f32_16x16x32_bf16 v[100:103], v[136:139], v[220:223], v[100:103]
	v_mfma_f32_16x16x32_bf16 v[92:95], v[144:147], v[220:223], v[92:95]
	v_mfma_f32_16x16x32_bf16 v[84:87], v[136:139], v[228:231], v[84:87]
	v_mfma_f32_16x16x32_bf16 v[76:79], v[144:147], v[228:231], v[76:79]
	s_setprio 0
	s_setprio 1
	v_mfma_f32_16x16x32_bf16 v[116:119], v[148:151], v[190:193], v[116:119]
	v_mfma_f32_16x16x32_bf16 v[108:111], v[164:167], v[190:193], v[108:111]
	v_mfma_f32_16x16x32_bf16 v[104:107], v[148:151], v[198:201], v[104:107]
	v_mfma_f32_16x16x32_bf16 v[96:99], v[164:167], v[198:201], v[96:99]
	v_mfma_f32_16x16x32_bf16 v[88:91], v[148:151], v[216:219], v[88:91]
	v_mfma_f32_16x16x32_bf16 v[80:83], v[164:167], v[216:219], v[80:83]
	v_mfma_f32_16x16x32_bf16 v[72:75], v[148:151], v[224:227], v[72:75]
	v_mfma_f32_16x16x32_bf16 v[68:71], v[164:167], v[224:227], v[68:71]
	v_mfma_f32_16x16x32_bf16 v[116:119], v[160:163], v[194:197], v[116:119]
	v_mfma_f32_16x16x32_bf16 v[108:111], v[182:185], v[194:197], v[108:111]
	v_mfma_f32_16x16x32_bf16 v[104:107], v[160:163], v[212:215], v[104:107]
	v_mfma_f32_16x16x32_bf16 v[96:99], v[182:185], v[212:215], v[96:99]
	v_mfma_f32_16x16x32_bf16 v[88:91], v[160:163], v[220:223], v[88:91]
	v_mfma_f32_16x16x32_bf16 v[80:83], v[182:185], v[220:223], v[80:83]
	v_mfma_f32_16x16x32_bf16 v[72:75], v[160:163], v[228:231], v[72:75]
	v_mfma_f32_16x16x32_bf16 v[68:71], v[182:185], v[228:231], v[68:71]
	s_setprio 0
	s_barrier
; #define PG8_STAGE(bufoff, gbase, voff) do { _Pragma("unroll") for (int _i = 0; _i < 2; ++_i) \
;         __builtin_amdgcn_global_load_lds((const unsigned*)((const char*)(gbase) + (voff)[_i]), (PG8_LAS unsigned*)(lds + (bufoff) + ldsw + _i * 8192), 16, 0, 0); } while (0)
; #define PG8_LDA(dst, b, h) do { _Pragma("unroll") for (int m = 0; m < 4; ++m) _Pragma("unroll") for (int k = 0; k < 2; ++k) dst[m][k] = *(const PG8_LAS bf16x8*)(lds + PG8_SA(b, h) + aoff + m * 2048 + k * 1024); } while (0)
; #define PG8_LDB(dst, b, h) do { _Pragma("unroll") for (int n = 0; n < 2; ++n) _Pragma("unroll") for (int k = 0; k < 2; ++k) dst[n][k] = *(const PG8_LAS bf16x8*)(lds + PG8_SB(b, h) + boff + n * 2048 + k * 1024); } while (0)
; #define PG8_MMA(ai, bj, At, Bt) do { __builtin_amdgcn_s_setprio(1); _Pragma("unroll") for (int m = 0; m < 4; ++m) _Pragma("unroll") for (int n = 0; n < 2; ++n) _Pragma("unroll") for (int k = 0; k < 2; ++k) \
;         acc[ai][bj][m][n] = __builtin_amdgcn_mfma_f32_16x16x32_bf16(Bt[n][k], At[m][k], acc[ai][bj][m][n], 0, 0, 0); __builtin_amdgcn_s_setprio(0); } while (0)
; #define PG8_WAIT_V(n) asm volatile("s_waitcnt vmcnt(" #n ")" ::: "memory")
; #define PG8_WAIT_L(n) asm volatile("s_waitcnt lgkmcnt(" #n ")" ::: "memory")
; #define PG8_BAR __builtin_amdgcn_s_barrier()
; #define PG8_SCHED __builtin_amdgcn_sched_barrier(0)
; template <class Epi, class Sched, bool ALIGN_EPI = false, bool SP2 = false>
; __device__ __forceinline__ void gemm_phase(PG8_LAS unsigned char* lds, const Gemm g, const Sched& S, const Epi& E, int wave_s) {
;     ...
;             PG8_LDA(At, 0, 1); PG8_STAGE(PG8_SB(0, 0), b2, voffB); PG8_STAGE(PG8_SB(0, 1), b2 + hstepB, voffB); PG8_STAGE(PG8_SA(0, 0), a2, voffA);
;             PG8_WAIT_V(8); PG8_WAIT_L(0); PG8_BAR; PG8_MMA(1, 0, At, B0); PG8_MMA(1, 1, At, B1); PG8_BAR; PG8_SCHED;
;             PG8_LDB(B0, 1, 0); PG8_LDB(B1, 1, 1); PG8_SCHED; PG8_LDA(At, 1, 0); PG8_STAGE(PG8_SA(0, 1), a2 + hstepA, voffA);
;             PG8_WAIT_V(8); PG8_WAIT_L(0); PG8_BAR; PG8_MMA(0, 0, At, B0); PG8_MMA(0, 1, At, B1); PG8_BAR; PG8_SCHED;
	s_add_i32 s24, s74, s48
	s_add_u32 s98, s38, s60
	s_addc_u32 s99, s39, s61
	s_mov_b32 m0, s24
	ds_read_b128 v[190:193], v188 offset:16384
	ds_read_b128 v[194:197], v188 offset:17408
	ds_read_b128 v[198:201], v188 offset:18432
	ds_read_b128 v[212:215], v188 offset:19456
	ds_read_b128 v[216:219], v188 offset:20480
	ds_read_b128 v[220:223], v188 offset:21504
	ds_read_b128 v[224:227], v188 offset:22528
	ds_read_b128 v[228:231], v188 offset:23552
	global_load_lds_dwordx4 v2, s[38:39]
	s_add_i32 m0, s24, 0x2000
	s_add_u32 s24, s38, 0x20000
	s_addc_u32 s25, s39, 0
	s_add_i32 s74, s75, s48
	global_load_lds_dwordx4 v0, s[38:39]
	s_mov_b32 m0, s74
	s_add_u32 s100, s42, s60
	s_addc_u32 s101, s43, s61
	s_nop 0
	global_load_lds_dwordx4 v2, s[24:25]
	s_add_i32 m0, s74, 0x2000
	s_nop 0
	global_load_lds_dwordx4 v0, s[24:25]
	s_mov_b32 m0, s49
	s_nop 0
	global_load_lds_dwordx4 v154, s[42:43]
	s_mov_b32 m0, s50
	s_nop 0
	global_load_lds_dwordx4 v152, s[42:43]
	s_waitcnt vmcnt(8)
	s_waitcnt lgkmcnt(0)
	s_barrier
	s_setprio 1
	s_waitcnt lgkmcnt(0)
	v_mfma_f32_16x16x32_bf16 v[64:67], v[132:135], v[190:193], v[64:67]
	v_mfma_f32_16x16x32_bf16 v[60:63], v[140:143], v[190:193], v[60:63]
	v_mfma_f32_16x16x32_bf16 v[52:55], v[132:135], v[198:201], v[52:55]
	v_mfma_f32_16x16x32_bf16 v[44:47], v[140:143], v[198:201], v[44:47]
	v_mfma_f32_16x16x32_bf16 v[36:39], v[132:135], v[216:219], v[36:39]
	v_mfma_f32_16x16x32_bf16 v[28:31], v[140:143], v[216:219], v[28:31]
	v_mfma_f32_16x16x32_bf16 v[20:23], v[132:135], v[224:227], v[20:23]
	v_mfma_f32_16x16x32_bf16 v[12:15], v[140:143], v[224:227], v[12:15]
	v_mfma_f32_16x16x32_bf16 v[64:67], v[136:139], v[194:197], v[64:67]
	v_mfma_f32_16x16x32_bf16 v[60:63], v[144:147], v[194:197], v[60:63]
	v_mfma_f32_16x16x32_bf16 v[52:55], v[136:139], v[212:215], v[52:55]
	v_mfma_f32_16x16x32_bf16 v[44:47], v[144:147], v[212:215], v[44:47]
	v_mfma_f32_16x16x32_bf16 v[36:39], v[136:139], v[220:223], v[36:39]
	v_mfma_f32_16x16x32_bf16 v[28:31], v[144:147], v[220:223], v[28:31]
	v_mfma_f32_16x16x32_bf16 v[20:23], v[136:139], v[228:231], v[20:23]
	v_mfma_f32_16x16x32_bf16 v[12:15], v[144:147], v[228:231], v[12:15]
	s_setprio 0
	s_setprio 1
	v_mfma_f32_16x16x32_bf16 v[56:59], v[148:151], v[190:193], v[56:59]
	v_mfma_f32_16x16x32_bf16 v[48:51], v[164:167], v[190:193], v[48:51]
	v_mfma_f32_16x16x32_bf16 v[40:43], v[148:151], v[198:201], v[40:43]
	v_mfma_f32_16x16x32_bf16 v[32:35], v[164:167], v[198:201], v[32:35]
	v_mfma_f32_16x16x32_bf16 v[24:27], v[148:151], v[216:219], v[24:27]
	v_mfma_f32_16x16x32_bf16 v[16:19], v[164:167], v[216:219], v[16:19]
	v_mfma_f32_16x16x32_bf16 v[8:11], v[148:151], v[224:227], v[8:11]
	v_mfma_f32_16x16x32_bf16 v[4:7], v[164:167], v[224:227], v[4:7]
	v_mfma_f32_16x16x32_bf16 v[56:59], v[160:163], v[194:197], v[56:59]
	v_mfma_f32_16x16x32_bf16 v[48:51], v[182:185], v[194:197], v[48:51]
	v_mfma_f32_16x16x32_bf16 v[40:43], v[160:163], v[212:215], v[40:43]
	v_mfma_f32_16x16x32_bf16 v[32:35], v[182:185], v[212:215], v[32:35]
	v_mfma_f32_16x16x32_bf16 v[24:27], v[160:163], v[220:223], v[24:27]
	v_mfma_f32_16x16x32_bf16 v[16:19], v[182:185], v[220:223], v[16:19]
	v_mfma_f32_16x16x32_bf16 v[8:11], v[160:163], v[228:231], v[8:11]
	v_mfma_f32_16x16x32_bf16 v[4:7], v[182:185], v[228:231], v[4:7]
	s_setprio 0
	s_barrier
	s_nop 0
	s_add_i32 s74, 0, 0x18000
	s_add_i32 s75, 0, 0x1c000
	v_add_u32_e32 v144, s74, v186
	v_add_u32_e32 v182, s75, v186
	ds_read_b128 v[132:135], v144
	ds_read_b128 v[136:139], v144 offset:1024
	ds_read_b128 v[140:143], v144 offset:2048
	ds_read_b128 v[144:147], v144 offset:3072
	ds_read_b128 v[148:151], v182
	ds_read_b128 v[160:163], v182 offset:1024
	ds_read_b128 v[164:167], v182 offset:2048
	ds_read_b128 v[182:185], v182 offset:3072
	s_add_u32 s24, s42, 0x4b0000
	s_addc_u32 s25, s43, 0
	s_mov_b32 m0, s51
	ds_read_b128 v[190:193], v188 offset:32768
	ds_read_b128 v[194:197], v188 offset:33792
	ds_read_b128 v[198:201], v188 offset:34816
	ds_read_b128 v[212:215], v188 offset:35840
	ds_read_b128 v[216:219], v188 offset:36864
	ds_read_b128 v[220:223], v188 offset:37888
	ds_read_b128 v[224:227], v188 offset:38912
	ds_read_b128 v[228:231], v188 offset:39936
	global_load_lds_dwordx4 v154, s[24:25]
	s_mov_b32 m0, s52
	s_nop 0
	global_load_lds_dwordx4 v152, s[24:25]
	s_waitcnt vmcnt(8)
	s_waitcnt lgkmcnt(0)
	s_barrier
; #define PG8_STAGE(bufoff, gbase, voff) do { _Pragma("unroll") for (int _i = 0; _i < 2; ++_i) \
;         __builtin_amdgcn_global_load_lds((const unsigned*)((const char*)(gbase) + (voff)[_i]), (PG8_LAS unsigned*)(lds + (bufoff) + ldsw + _i * 8192), 16, 0, 0); } while (0)
; #define PG8_LDA(dst, b, h) do { _Pragma("unroll") for (int m = 0; m < 4; ++m) _Pragma("unroll") for (int k = 0; k < 2; ++k) dst[m][k] = *(const PG8_LAS bf16x8*)(lds + PG8_SA(b, h) + aoff + m * 2048 + k * 1024); } while (0)
; #define PG8_MMA(ai, bj, At, Bt) do { __builtin_amdgcn_s_setprio(1); _Pragma("unroll") for (int m = 0; m < 4; ++m) _Pragma("unroll") for (int n = 0; n < 2; ++n) _Pragma("unroll") for (int k = 0; k < 2; ++k) \
;         acc[ai][bj][m][n] = __builtin_amdgcn_mfma_f32_16x16x32_bf16(Bt[n][k], At[m][k], acc[ai][bj][m][n], 0, 0, 0); __builtin_amdgcn_s_setprio(0); } while (0)
; #define PG8_WAIT_V(n) asm volatile("s_waitcnt vmcnt(" #n ")" ::: "memory")
; #define PG8_WAIT_L(n) asm volatile("s_waitcnt lgkmcnt(" #n ")" ::: "memory")
; #define PG8_BAR __builtin_amdgcn_s_barrier()
; #define PG8_SCHED __builtin_amdgcn_sched_barrier(0)
; template <class Epi, class Sched, bool ALIGN_EPI = false, bool SP2 = false>
; __device__ __forceinline__ void gemm_phase(PG8_LAS unsigned char* lds, const Gemm g, const Sched& S, const Epi& E, int wave_s) {
;     ...
;             PG8_WAIT_V(8); PG8_WAIT_L(0); PG8_BAR; PG8_MMA(0, 0, At, B0); PG8_MMA(0, 1, At, B1); PG8_BAR; PG8_SCHED;
;             PG8_LDA(At, 1, 1); PG8_STAGE(PG8_SB(1, 0), b3, voffB); PG8_STAGE(PG8_SB(1, 1), b3 + hstepB, voffB); PG8_STAGE(PG8_SA(1, 0), a3, voffA);
;             PG8_WAIT_V(8); PG8_WAIT_L(0); PG8_BAR; PG8_MMA(1, 0, At, B0); PG8_MMA(1, 1, At, B1); PG8_BAR; PG8_SCHED;
;     ...
;         if constexpr (ALIGN_EPI) { if (wr == 0) PG8_BAR; }
	s_setprio 1
	s_waitcnt lgkmcnt(0)
	v_mfma_f32_16x16x32_bf16 v[128:131], v[132:135], v[190:193], v[128:131]
	v_mfma_f32_16x16x32_bf16 v[124:127], v[140:143], v[190:193], v[124:127]
	v_mfma_f32_16x16x32_bf16 v[120:123], v[132:135], v[198:201], v[120:123]
	v_mfma_f32_16x16x32_bf16 v[112:115], v[140:143], v[198:201], v[112:115]
	v_mfma_f32_16x16x32_bf16 v[100:103], v[132:135], v[216:219], v[100:103]
	v_mfma_f32_16x16x32_bf16 v[92:95], v[140:143], v[216:219], v[92:95]
	v_mfma_f32_16x16x32_bf16 v[84:87], v[132:135], v[224:227], v[84:87]
	v_mfma_f32_16x16x32_bf16 v[76:79], v[140:143], v[224:227], v[76:79]
	v_mfma_f32_16x16x32_bf16 v[128:131], v[136:139], v[194:197], v[128:131]
	v_mfma_f32_16x16x32_bf16 v[124:127], v[144:147], v[194:197], v[124:127]
	v_mfma_f32_16x16x32_bf16 v[120:123], v[136:139], v[212:215], v[120:123]
	v_mfma_f32_16x16x32_bf16 v[112:115], v[144:147], v[212:215], v[112:115]
	v_mfma_f32_16x16x32_bf16 v[100:103], v[136:139], v[220:223], v[100:103]
	v_mfma_f32_16x16x32_bf16 v[92:95], v[144:147], v[220:223], v[92:95]
	v_mfma_f32_16x16x32_bf16 v[84:87], v[136:139], v[228:231], v[84:87]
	v_mfma_f32_16x16x32_bf16 v[76:79], v[144:147], v[228:231], v[76:79]
	s_setprio 0
	s_setprio 1
	v_mfma_f32_16x16x32_bf16 v[116:119], v[148:151], v[190:193], v[116:119]
	v_mfma_f32_16x16x32_bf16 v[108:111], v[164:167], v[190:193], v[108:111]
	v_mfma_f32_16x16x32_bf16 v[104:107], v[148:151], v[198:201], v[104:107]
	v_mfma_f32_16x16x32_bf16 v[96:99], v[164:167], v[198:201], v[96:99]
	v_mfma_f32_16x16x32_bf16 v[88:91], v[148:151], v[216:219], v[88:91]
	v_mfma_f32_16x16x32_bf16 v[80:83], v[164:167], v[216:219], v[80:83]
	v_mfma_f32_16x16x32_bf16 v[72:75], v[148:151], v[224:227], v[72:75]
	v_mfma_f32_16x16x32_bf16 v[68:71], v[164:167], v[224:227], v[68:71]
	v_mfma_f32_16x16x32_bf16 v[116:119], v[160:163], v[194:197], v[116:119]
	v_mfma_f32_16x16x32_bf16 v[108:111], v[182:185], v[194:197], v[108:111]
	v_mfma_f32_16x16x32_bf16 v[104:107], v[160:163], v[212:215], v[104:107]
	v_mfma_f32_16x16x32_bf16 v[96:99], v[182:185], v[212:215], v[96:99]
	v_mfma_f32_16x16x32_bf16 v[88:91], v[160:163], v[220:223], v[88:91]
	v_mfma_f32_16x16x32_bf16 v[80:83], v[182:185], v[220:223], v[80:83]
	v_mfma_f32_16x16x32_bf16 v[72:75], v[160:163], v[228:231], v[72:75]
	v_mfma_f32_16x16x32_bf16 v[68:71], v[182:185], v[228:231], v[68:71]
	s_setprio 0
	s_barrier
	s_add_i32 s24, s74, s48
	s_mov_b32 m0, s24
	ds_read_b128 v[190:193], v188 offset:49152
	ds_read_b128 v[194:197], v188 offset:50176
	ds_read_b128 v[198:201], v188 offset:51200
	ds_read_b128 v[212:215], v188 offset:52224
	ds_read_b128 v[216:219], v188 offset:53248
	ds_read_b128 v[220:223], v188 offset:54272
	ds_read_b128 v[224:227], v188 offset:55296
	ds_read_b128 v[228:231], v188 offset:56320
	global_load_lds_dwordx4 v2, s[98:99]
	s_add_i32 m0, s24, 0x2000
	s_add_u32 s24, s38, 0x20080
	s_addc_u32 s25, s39, 0
	s_add_i32 s38, s75, s48
	global_load_lds_dwordx4 v0, s[98:99]
	s_mov_b32 m0, s38
	s_nop 0
	global_load_lds_dwordx4 v2, s[24:25]
	s_add_i32 m0, s38, 0x2000
	s_nop 0
	global_load_lds_dwordx4 v0, s[24:25]
	s_mov_b32 m0, s53
	s_nop 0
	global_load_lds_dwordx4 v154, s[100:101]
	s_mov_b32 m0, s54
	s_nop 0
	global_load_lds_dwordx4 v152, s[100:101]
	s_waitcnt vmcnt(8)
	s_waitcnt lgkmcnt(0)
	s_barrier
	s_setprio 1
	s_waitcnt lgkmcnt(0)
	v_mfma_f32_16x16x32_bf16 v[64:67], v[132:135], v[190:193], v[64:67]
	v_mfma_f32_16x16x32_bf16 v[60:63], v[140:143], v[190:193], v[60:63]
	v_mfma_f32_16x16x32_bf16 v[52:55], v[132:135], v[198:201], v[52:55]
	v_mfma_f32_16x16x32_bf16 v[44:47], v[140:143], v[198:201], v[44:47]
	v_mfma_f32_16x16x32_bf16 v[36:39], v[132:135], v[216:219], v[36:39]
	v_mfma_f32_16x16x32_bf16 v[28:31], v[140:143], v[216:219], v[28:31]
	v_mfma_f32_16x16x32_bf16 v[20:23], v[132:135], v[224:227], v[20:23]
	v_mfma_f32_16x16x32_bf16 v[12:15], v[140:143], v[224:227], v[12:15]
	v_mfma_f32_16x16x32_bf16 v[64:67], v[136:139], v[194:197], v[64:67]
	v_mfma_f32_16x16x32_bf16 v[60:63], v[144:147], v[194:197], v[60:63]
	v_mfma_f32_16x16x32_bf16 v[52:55], v[136:139], v[212:215], v[52:55]
	v_mfma_f32_16x16x32_bf16 v[44:47], v[144:147], v[212:215], v[44:47]
	v_mfma_f32_16x16x32_bf16 v[36:39], v[136:139], v[220:223], v[36:39]
	v_mfma_f32_16x16x32_bf16 v[28:31], v[144:147], v[220:223], v[28:31]
	v_mfma_f32_16x16x32_bf16 v[20:23], v[136:139], v[228:231], v[20:23]
	v_mfma_f32_16x16x32_bf16 v[12:15], v[144:147], v[228:231], v[12:15]
	s_setprio 0
	s_setprio 1
	v_mfma_f32_16x16x32_bf16 v[56:59], v[148:151], v[190:193], v[56:59]
	v_mfma_f32_16x16x32_bf16 v[48:51], v[164:167], v[190:193], v[48:51]
	v_mfma_f32_16x16x32_bf16 v[40:43], v[148:151], v[198:201], v[40:43]
	v_mfma_f32_16x16x32_bf16 v[32:35], v[164:167], v[198:201], v[32:35]
	v_mfma_f32_16x16x32_bf16 v[24:27], v[148:151], v[216:219], v[24:27]
	v_mfma_f32_16x16x32_bf16 v[16:19], v[164:167], v[216:219], v[16:19]
	v_mfma_f32_16x16x32_bf16 v[8:11], v[148:151], v[224:227], v[8:11]
	v_mfma_f32_16x16x32_bf16 v[4:7], v[164:167], v[224:227], v[4:7]
	v_mfma_f32_16x16x32_bf16 v[56:59], v[160:163], v[194:197], v[56:59]
	v_mfma_f32_16x16x32_bf16 v[48:51], v[182:185], v[194:197], v[48:51]
	v_mfma_f32_16x16x32_bf16 v[40:43], v[160:163], v[212:215], v[40:43]
	v_mfma_f32_16x16x32_bf16 v[32:35], v[182:185], v[212:215], v[32:35]
	v_mfma_f32_16x16x32_bf16 v[24:27], v[160:163], v[220:223], v[24:27]
	v_mfma_f32_16x16x32_bf16 v[16:19], v[182:185], v[220:223], v[16:19]
	v_mfma_f32_16x16x32_bf16 v[8:11], v[160:163], v[228:231], v[8:11]
	v_mfma_f32_16x16x32_bf16 v[4:7], v[182:185], v[228:231], v[4:7]
	s_setprio 0
	s_barrier
	s_add_i32 s67, s67, 2
	s_add_u32 s59, s59, 0x100
	s_addc_u32 s66, s66, 0
	s_cmp_gt_u32 s67, 5
	s_mov_b64 s[24:25], s[26:27]
	s_cbranch_scc0 .LBB0_568
	s_and_b64 vcc, exec, s[16:17]
	s_cbranch_vccz .LBB0_571
	s_barrier

; template <class Epi, class Sched, bool ALIGN_EPI = false, bool SP2 = false>
; __device__ __forceinline__ void gemm_phase(PG8_LAS unsigned char* lds, const Gemm g, const Sched& S, const Epi& E, int wave_s) {
;     ...
;         const bool has_next = S.next(ui + 1, nxt);
;         const char* nA = has_next ? (const char*)g.A + (size_t)nxt.pm * tstepA : cA; const char* nB = has_next ? (const char*)g.Bt + (size_t)nxt.pn * tstepB : cB;
;         for (int t = 0; t < nt; t += 2) {
;             const bool last = (t == nt - 2);
;             const char* a1 = cA + (size_t)(t + 1) * kstep;
;             const char* a2 = last ? nA : cA + (size_t)(t + 2) * kstep; const char* b2 = last ? nB : cB + (size_t)(t + 2) * kstep;
;     ...
;         for (int a = 0; a < 2; ++a)
; #pragma unroll
;             for (int b = 0; b < 2; ++b)
; #pragma unroll
;                 for (int m = 0; m < 4; ++m)
; #pragma unroll
;                     for (int n = 0; n < 2; ++n) acc[a][b][m][n] = (f32x4){0.f, 0.f, 0.f, 0.f};
.LBB0_660:
	s_ashr_i32 s7, s6, 31
	s_lshl_b64 s[16:17], s[6:7], 20
	s_add_u32 s22, s2, s16
	s_addc_u32 s23, s30, s17
	s_and_b64 s[16:17], s[36:37], exec
	s_cselect_b32 s7, s23, s27
	s_cselect_b32 s57, s22, s26
	s_ashr_i32 s5, s4, 31
	s_lshl_b64 s[16:17], s[4:5], 20
	s_add_u32 s16, s44, s16
	s_addc_u32 s17, s45, s17
	s_and_b64 s[42:43], s[36:37], exec
	s_cselect_b32 s5, s17, s19
	s_cselect_b32 s58, s16, s18
	s_add_u32 s59, s18, 0x100
	s_addc_u32 s66, s19, 0
	s_add_u32 s18, s26, 0x80080
	s_addc_u32 s19, s27, 0
	s_mov_b32 s67, -2
	s_nop 0
	s_nop 0
	s_nop 0
	s_nop 0
	s_nop 0
	s_nop 0
	s_nop 0
	s_nop 0
	s_nop 0
	s_nop 0
	s_nop 0
	s_nop 0
	v_mov_b64_e32 v[4:5], 0
	v_mov_b64_e32 v[6:7], 0
	v_mov_b64_e32 v[8:9], 0
	v_mov_b64_e32 v[10:11], 0
	v_mov_b64_e32 v[12:13], 0
	v_mov_b64_e32 v[14:15], 0
	v_mov_b64_e32 v[16:17], 0
	v_mov_b64_e32 v[18:19], 0
	v_mov_b64_e32 v[20:21], 0
	v_mov_b64_e32 v[22:23], 0
	v_mov_b64_e32 v[24:25], 0
	v_mov_b64_e32 v[26:27], 0
	v_mov_b64_e32 v[28:29], 0
	v_mov_b64_e32 v[30:31], 0
	v_mov_b64_e32 v[32:33], 0
	v_mov_b64_e32 v[34:35], 0
	v_mov_b64_e32 v[36:37], 0
	v_mov_b64_e32 v[38:39], 0
	v_mov_b64_e32 v[40:41], 0
	v_mov_b64_e32 v[42:43], 0
	v_mov_b64_e32 v[44:45], 0
	v_mov_b64_e32 v[46:47], 0
	v_mov_b64_e32 v[48:49], 0
	v_mov_b64_e32 v[50:51], 0
	v_mov_b64_e32 v[52:53], 0
	v_mov_b64_e32 v[54:55], 0
	v_mov_b64_e32 v[56:57], 0
	v_mov_b64_e32 v[58:59], 0
	v_mov_b64_e32 v[60:61], 0
	v_mov_b64_e32 v[62:63], 0
	v_mov_b64_e32 v[64:65], 0
	v_mov_b64_e32 v[66:67], 0
	v_mov_b64_e32 v[68:69], 0
	v_mov_b64_e32 v[70:71], 0
	v_mov_b64_e32 v[72:73], 0
	v_mov_b64_e32 v[74:75], 0
	v_mov_b64_e32 v[76:77], 0
	v_mov_b64_e32 v[78:79], 0
	v_mov_b64_e32 v[80:81], 0
	v_mov_b64_e32 v[82:83], 0
	v_mov_b64_e32 v[84:85], 0
	v_mov_b64_e32 v[86:87], 0
	v_mov_b64_e32 v[88:89], 0
	v_mov_b64_e32 v[90:91], 0
	v_mov_b64_e32 v[92:93], 0
	v_mov_b64_e32 v[94:95], 0
	v_mov_b64_e32 v[96:97], 0
	v_mov_b64_e32 v[98:99], 0
	v_mov_b64_e32 v[100:101], 0
	v_mov_b64_e32 v[102:103], 0
	v_mov_b64_e32 v[104:105], 0
	v_mov_b64_e32 v[106:107], 0
	v_mov_b64_e32 v[124:125], 0
	v_mov_b64_e32 v[126:127], 0
	v_mov_b64_e32 v[128:129], 0
	v_mov_b64_e32 v[130:131], 0
	v_mov_b64_e32 v[132:133], 0
	v_mov_b64_e32 v[134:135], 0
	v_mov_b64_e32 v[136:137], 0
	v_mov_b64_e32 v[138:139], 0
	v_mov_b64_e32 v[140:141], 0
	v_mov_b64_e32 v[142:143], 0
	v_mov_b64_e32 v[144:145], 0
	v_mov_b64_e32 v[146:147], 0

; template <class Epi, class Sched, bool ALIGN_EPI = false, bool SP2 = false>
; __device__ __forceinline__ void gemm_phase(PG8_LAS unsigned char* lds, const Gemm g, const Sched& S, const Epi& E, int wave_s) {
;     ...
;         for (int a = 0; a < 2; ++a)
; #pragma unroll
;             for (int b = 0; b < 2; ++b)
; #pragma unroll
;                 for (int m = 0; m < 4; ++m)
; #pragma unroll
;                     for (int n = 0; n < 2; ++n) acc[a][b][m][n] = (f32x4){0.f, 0.f, 0.f, 0.f};
.LBB0_862:
	s_add_u32 s36, s22, 0x100
	s_addc_u32 s37, s23, 0
	s_mov_b32 s53, -2
	s_waitcnt vmcnt(0) lgkmcnt(0)
	s_nop 0
	s_nop 0
	s_nop 0
	s_nop 0
	s_nop 0
	s_nop 0
	s_nop 0
	s_nop 0
	v_mov_b64_e32 v[4:5], 0
	v_mov_b64_e32 v[6:7], 0
	v_mov_b64_e32 v[8:9], 0
	v_mov_b64_e32 v[10:11], 0
	v_mov_b64_e32 v[12:13], 0
	v_mov_b64_e32 v[14:15], 0
	v_mov_b64_e32 v[16:17], 0
	v_mov_b64_e32 v[18:19], 0
	v_mov_b64_e32 v[20:21], 0
	v_mov_b64_e32 v[22:23], 0
	v_mov_b64_e32 v[24:25], 0
	v_mov_b64_e32 v[26:27], 0
	v_mov_b64_e32 v[28:29], 0
	v_mov_b64_e32 v[30:31], 0
	v_mov_b64_e32 v[32:33], 0
	v_mov_b64_e32 v[34:35], 0
	v_mov_b64_e32 v[36:37], 0
	v_mov_b64_e32 v[38:39], 0
	v_mov_b64_e32 v[40:41], 0
	v_mov_b64_e32 v[42:43], 0
	v_mov_b64_e32 v[44:45], 0
	v_mov_b64_e32 v[46:47], 0
	v_mov_b64_e32 v[48:49], 0
	v_mov_b64_e32 v[50:51], 0
	v_mov_b64_e32 v[52:53], 0
	v_mov_b64_e32 v[54:55], 0
	v_mov_b64_e32 v[56:57], 0
	v_mov_b64_e32 v[58:59], 0
	v_mov_b64_e32 v[60:61], 0
	v_mov_b64_e32 v[62:63], 0
	v_mov_b64_e32 v[64:65], 0
	v_mov_b64_e32 v[66:67], 0
	v_mov_b64_e32 v[68:69], 0
	v_mov_b64_e32 v[70:71], 0
	v_mov_b64_e32 v[72:73], 0
	v_mov_b64_e32 v[74:75], 0
	v_mov_b64_e32 v[76:77], 0
	v_mov_b64_e32 v[78:79], 0
	v_mov_b64_e32 v[80:81], 0
	v_mov_b64_e32 v[82:83], 0
	v_mov_b64_e32 v[84:85], 0
	v_mov_b64_e32 v[86:87], 0
	v_mov_b64_e32 v[88:89], 0
	v_mov_b64_e32 v[90:91], 0
	v_mov_b64_e32 v[92:93], 0
	v_mov_b64_e32 v[94:95], 0
	v_mov_b64_e32 v[96:97], 0
	v_mov_b64_e32 v[98:99], 0
	v_mov_b64_e32 v[100:101], 0
	v_mov_b64_e32 v[102:103], 0
	v_mov_b64_e32 v[104:105], 0
	v_mov_b64_e32 v[106:107], 0
	v_mov_b64_e32 v[108:109], 0
	v_mov_b64_e32 v[110:111], 0
	v_mov_b64_e32 v[112:113], 0
	v_mov_b64_e32 v[114:115], 0
	v_mov_b64_e32 v[116:117], 0
	v_mov_b64_e32 v[118:119], 0
	v_mov_b64_e32 v[120:121], 0
	v_mov_b64_e32 v[122:123], 0
	v_mov_b64_e32 v[124:125], 0
	v_mov_b64_e32 v[126:127], 0
	v_mov_b64_e32 v[128:129], 0
	v_mov_b64_e32 v[130:131], 0
